# v044 + attention: cross-half row-max exchange via v_permlane32_swap instead of ds_bpermute + lgkmcnt wait
# baseline (speedup 1.0000x reference)
; __device__ __forceinline__ void attn_phase(LAS unsigned char* lds, const bf16* Q, const bf16* Kb, const bf16* VT, const bf16* Kc, const bf16* VcT, bf16* O, const float* relb, int gw, int ngw, int tid) {
;     ...
;                 float mx = sc[0];
; #pragma unroll
;                 for (int r = 1; r < 16; ++r) mx = fmaxf(mx, sc[r]);
;                 mx = fmaxf(mx, __shfl_xor(mx, 32));
;                 if (__any(mx > mrun[qb] + 8.0f)) {
;                     const float mnew = fmaxf(mrun[qb], mx), alpha = __builtin_amdgcn_exp2f(mrun[qb] - mnew); mrun[qb] = mnew; lrun[qb] *= alpha;
; #pragma unroll
;                     for (int db = 0; db < 2; ++db)
; #pragma unroll
;                         for (int r = 0; r < 16; ++r) o[qb][db][r] *= alpha; }
.LBB0_275:
	s_nop 10
	v_max_f32_e32 v190, v67, v67
	v_max_f32_e32 v191, v66, v66
	v_max_f32_e32 v190, v191, v190
	v_max3_f32 v190, v190, v68, v69
	v_max3_f32 v190, v190, v70, v71
	v_max3_f32 v190, v190, v72, v73
	v_max3_f32 v190, v190, v74, v75
	v_max3_f32 v190, v190, v76, v77
	v_max3_f32 v190, v190, v78, v79
	v_max3_f32 v190, v190, v80, v81
	v_mov_b32_e32 v191, v190
	s_nop 1
	v_permlane32_swap_b32_e32 v190, v191
	v_max_f32_e32 v190, v190, v191
	v_add_f32_e32 v191, 0x41000000, v188
	v_cmp_gt_f32_e32 vcc, v190, v191
	s_cbranch_vccz .LBB0_277
	v_max_f32_e32 v190, v190, v190
	v_max_f32_e32 v191, v188, v188
	v_max_f32_e32 v190, v191, v190
	v_sub_f32_e32 v188, v188, v190
	v_exp_f32_e32 v188, v188
	s_nop 0
	v_mul_f32_e32 v187, v187, v188
	v_pk_mul_f32 v[64:65], v[64:65], v[188:189] op_sel_hi:[1,0]
	v_pk_mul_f32 v[62:63], v[62:63], v[188:189] op_sel_hi:[1,0]
	v_pk_mul_f32 v[60:61], v[60:61], v[188:189] op_sel_hi:[1,0]
	v_pk_mul_f32 v[58:59], v[58:59], v[188:189] op_sel_hi:[1,0]
	v_pk_mul_f32 v[56:57], v[56:57], v[188:189] op_sel_hi:[1,0]
	v_pk_mul_f32 v[54:55], v[54:55], v[188:189] op_sel_hi:[1,0]
	v_pk_mul_f32 v[52:53], v[52:53], v[188:189] op_sel_hi:[1,0]
	v_pk_mul_f32 v[50:51], v[50:51], v[188:189] op_sel_hi:[1,0]
	v_pk_mul_f32 v[48:49], v[48:49], v[188:189] op_sel_hi:[1,0]
	v_pk_mul_f32 v[46:47], v[46:47], v[188:189] op_sel_hi:[1,0]
	v_pk_mul_f32 v[44:45], v[44:45], v[188:189] op_sel_hi:[1,0]
	v_pk_mul_f32 v[42:43], v[42:43], v[188:189] op_sel_hi:[1,0]
	v_pk_mul_f32 v[40:41], v[40:41], v[188:189] op_sel_hi:[1,0]
	v_pk_mul_f32 v[38:39], v[38:39], v[188:189] op_sel_hi:[1,0]
	v_pk_mul_f32 v[36:37], v[36:37], v[188:189] op_sel_hi:[1,0]
	v_pk_mul_f32 v[34:35], v[34:35], v[188:189] op_sel_hi:[1,0]
	v_mov_b32_e32 v188, v190

; __device__ __forceinline__ void attn_phase(LAS unsigned char* lds, const bf16* Q, const bf16* Kb, const bf16* VT, const bf16* Kc, const bf16* VcT, bf16* O, const float* relb, int gw, int ngw, int tid) {
;     ...
;                 float mx = sc[0];
; #pragma unroll
;                 for (int r = 1; r < 16; ++r) mx = fmaxf(mx, sc[r]);
;                 mx = fmaxf(mx, __shfl_xor(mx, 32));
;                 if (__any(mx > mrun[qb] + 8.0f)) {
;                     const float mnew = fmaxf(mrun[qb], mx), alpha = __builtin_amdgcn_exp2f(mrun[qb] - mnew); mrun[qb] = mnew; lrun[qb] *= alpha;
; #pragma unroll
;                     for (int db = 0; db < 2; ++db)
; #pragma unroll
;                         for (int r = 0; r < 16; ++r) o[qb][db][r] *= alpha; }
.LBB0_279:
	s_nop 10
	v_max_f32_e32 v1, v67, v67
	v_max_f32_e32 v162, v66, v66
	v_max_f32_e32 v1, v162, v1
	v_max3_f32 v1, v1, v68, v69
	v_max3_f32 v1, v1, v70, v71
	v_max3_f32 v1, v1, v72, v73
	v_max3_f32 v1, v1, v74, v75
	v_max3_f32 v1, v1, v76, v77
	v_max3_f32 v1, v1, v78, v79
	v_max3_f32 v1, v1, v80, v81
	v_mov_b32_e32 v162, v1
	s_nop 1
	v_permlane32_swap_b32_e32 v1, v162
	v_max_f32_e32 v1, v1, v162
	v_add_f32_e32 v162, 0x41000000, v189
	v_cmp_gt_f32_e32 vcc, v1, v162
	s_cbranch_vccz .LBB0_281
	v_max_f32_e32 v1, v1, v1
	v_max_f32_e32 v162, v189, v189
	v_max_f32_e32 v1, v162, v1
	v_sub_f32_e32 v162, v189, v1
	v_exp_f32_e32 v162, v162
	v_mov_b32_e32 v189, v1
	v_mul_f32_e32 v186, v186, v162
	v_pk_mul_f32 v[32:33], v[32:33], v[162:163] op_sel_hi:[1,0]
	v_pk_mul_f32 v[30:31], v[30:31], v[162:163] op_sel_hi:[1,0]
	v_pk_mul_f32 v[28:29], v[28:29], v[162:163] op_sel_hi:[1,0]
	v_pk_mul_f32 v[26:27], v[26:27], v[162:163] op_sel_hi:[1,0]
	v_pk_mul_f32 v[24:25], v[24:25], v[162:163] op_sel_hi:[1,0]
	v_pk_mul_f32 v[22:23], v[22:23], v[162:163] op_sel_hi:[1,0]
	v_pk_mul_f32 v[20:21], v[20:21], v[162:163] op_sel_hi:[1,0]
	v_pk_mul_f32 v[18:19], v[18:19], v[162:163] op_sel_hi:[1,0]
	v_pk_mul_f32 v[16:17], v[16:17], v[162:163] op_sel_hi:[1,0]
	v_pk_mul_f32 v[14:15], v[14:15], v[162:163] op_sel_hi:[1,0]
	v_pk_mul_f32 v[12:13], v[12:13], v[162:163] op_sel_hi:[1,0]
	v_pk_mul_f32 v[10:11], v[10:11], v[162:163] op_sel_hi:[1,0]
	v_pk_mul_f32 v[8:9], v[8:9], v[162:163] op_sel_hi:[1,0]
	v_pk_mul_f32 v[6:7], v[6:7], v[162:163] op_sel_hi:[1,0]
	v_pk_mul_f32 v[4:5], v[4:5], v[162:163] op_sel_hi:[1,0]
	v_pk_mul_f32 v[2:3], v[2:3], v[162:163] op_sel_hi:[1,0]
